# phase 1: layer-1 weight conversion tiles rebalanced (the 64 workgroups with a 6th GEMM tile and no PLE GEMM take the last 192 tiles)
# baseline (speedup 1.0000x reference)
.LBB0_522:
	s_movk_i32 s98, 0x9c0
	s_branch .Lwc_go
.Lwc_heavy:
	s_add_u32 s8, s92, 0x2500000
	s_addc_u32 s9, s93, 0
	s_movk_i32 s40, 64
	s_add_i32 s41, s97, 0x500
	s_movk_i32 s98, 0xa80

.LBB0_525:
	s_add_i32 s20, s20, s40
	s_add_i32 s21, s21, s22
	s_add_i32 s25, s25, s26
	s_cmp_lt_i32 s20, s98
	v_add_u32_e32 v62, s24, v62
	s_waitcnt vmcnt(63) expcnt(7) lgkmcnt(15)
	s_cbranch_scc0 .LBB0_699
